# first (redundant on the hot path) accumulator zeroing run of each GEMM tile loop moved into a cold block
# speedup vs baseline: 1.0617x; 1.0083x over previous
.LBB0_202:
	s_andn2_b64 vcc, exec, s[50:51]
	s_cbranch_vccnz .Lcoldzero_1
	s_add_u32 s10, s6, 0x100
	s_addc_u32 s11, s7, 0
	s_add_u32 s6, s8, 0x80
	v_mov_b32_e32 v4, 0
	s_addc_u32 s7, s9, 0
	s_mov_b32 s8, 0
	v_mov_b32_e32 v5, v4
	v_mov_b64_e32 v[6:7], 0
	v_mov_b64_e32 v[12:13], 0
	v_mov_b64_e32 v[14:15], 0
	v_mov_b64_e32 v[20:21], 0
	v_mov_b64_e32 v[22:23], 0
	v_mov_b64_e32 v[28:29], 0
	v_mov_b64_e32 v[30:31], 0
	v_mov_b64_e32 v[36:37], 0
	v_mov_b64_e32 v[38:39], 0
	v_mov_b64_e32 v[44:45], 0
	v_mov_b64_e32 v[46:47], 0
	v_mov_b64_e32 v[52:53], 0
	v_mov_b64_e32 v[54:55], 0
	v_mov_b64_e32 v[60:61], 0
	v_mov_b64_e32 v[62:63], 0
	v_mov_b64_e32 v[0:1], 0
	v_mov_b64_e32 v[2:3], 0
	v_mov_b64_e32 v[8:9], 0
	v_mov_b64_e32 v[10:11], 0
	v_mov_b64_e32 v[16:17], 0
	v_mov_b64_e32 v[18:19], 0
	v_mov_b64_e32 v[24:25], 0
	v_mov_b64_e32 v[26:27], 0
	v_mov_b64_e32 v[32:33], 0
	v_mov_b64_e32 v[34:35], 0
	v_mov_b64_e32 v[40:41], 0
	v_mov_b64_e32 v[42:43], 0
	v_mov_b64_e32 v[48:49], 0
	v_mov_b64_e32 v[50:51], 0
	v_mov_b64_e32 v[56:57], 0
	v_mov_b64_e32 v[58:59], 0
	v_mov_b64_e32 v[68:69], 0
	v_mov_b64_e32 v[70:71], 0
	v_mov_b64_e32 v[76:77], 0
	v_mov_b64_e32 v[78:79], 0
	v_mov_b64_e32 v[84:85], 0
	v_mov_b64_e32 v[86:87], 0
	v_mov_b64_e32 v[92:93], 0
	v_mov_b64_e32 v[94:95], 0
	v_mov_b64_e32 v[100:101], 0
	v_mov_b64_e32 v[102:103], 0
	v_mov_b64_e32 v[108:109], 0
	v_mov_b64_e32 v[110:111], 0
	v_mov_b64_e32 v[116:117], 0
	v_mov_b64_e32 v[118:119], 0
	v_mov_b64_e32 v[124:125], 0
	v_mov_b64_e32 v[126:127], 0
	v_mov_b64_e32 v[64:65], 0
	v_mov_b64_e32 v[66:67], 0
	v_mov_b64_e32 v[72:73], 0
	v_mov_b64_e32 v[74:75], 0
	v_mov_b64_e32 v[80:81], 0
	v_mov_b64_e32 v[82:83], 0
	v_mov_b64_e32 v[88:89], 0
	v_mov_b64_e32 v[90:91], 0
	v_mov_b64_e32 v[96:97], 0
	v_mov_b64_e32 v[98:99], 0
	v_mov_b64_e32 v[104:105], 0
	v_mov_b64_e32 v[106:107], 0
	v_mov_b64_e32 v[112:113], 0
	v_mov_b64_e32 v[114:115], 0
	v_mov_b64_e32 v[120:121], 0
	v_mov_b64_e32 v[122:123], 0

.Lcoldzero_1:
	v_mov_b32_e32 v123, 0
	v_mov_b32_e32 v122, v123
	v_mov_b64_e32 v[120:121], 0
	v_mov_b64_e32 v[114:115], 0
	v_mov_b64_e32 v[112:113], 0
	v_mov_b64_e32 v[106:107], 0
	v_mov_b64_e32 v[104:105], 0
	v_mov_b64_e32 v[98:99], 0
	v_mov_b64_e32 v[96:97], 0
	v_mov_b64_e32 v[90:91], 0
	v_mov_b64_e32 v[88:89], 0
	v_mov_b64_e32 v[82:83], 0
	v_mov_b64_e32 v[80:81], 0
	v_mov_b64_e32 v[74:75], 0
	v_mov_b64_e32 v[72:73], 0
	v_mov_b64_e32 v[66:67], 0
	v_mov_b64_e32 v[64:65], 0
	v_mov_b64_e32 v[126:127], 0
	v_mov_b64_e32 v[124:125], 0
	v_mov_b64_e32 v[118:119], 0
	v_mov_b64_e32 v[116:117], 0
	v_mov_b64_e32 v[110:111], 0
	v_mov_b64_e32 v[108:109], 0
	v_mov_b64_e32 v[102:103], 0
	v_mov_b64_e32 v[100:101], 0
	v_mov_b64_e32 v[94:95], 0
	v_mov_b64_e32 v[92:93], 0
	v_mov_b64_e32 v[86:87], 0
	v_mov_b64_e32 v[84:85], 0
	v_mov_b64_e32 v[78:79], 0
	v_mov_b64_e32 v[76:77], 0
	v_mov_b64_e32 v[70:71], 0
	v_mov_b64_e32 v[68:69], 0
	v_mov_b64_e32 v[58:59], 0
	v_mov_b64_e32 v[56:57], 0
	v_mov_b64_e32 v[50:51], 0
	v_mov_b64_e32 v[48:49], 0
	v_mov_b64_e32 v[42:43], 0
	v_mov_b64_e32 v[40:41], 0
	v_mov_b64_e32 v[34:35], 0
	v_mov_b64_e32 v[32:33], 0
	v_mov_b64_e32 v[26:27], 0
	v_mov_b64_e32 v[24:25], 0
	v_mov_b64_e32 v[18:19], 0
	v_mov_b64_e32 v[16:17], 0
	v_mov_b64_e32 v[10:11], 0
	v_mov_b64_e32 v[8:9], 0
	v_mov_b64_e32 v[2:3], 0
	v_mov_b64_e32 v[0:1], 0
	v_mov_b64_e32 v[62:63], 0
	v_mov_b64_e32 v[60:61], 0
	v_mov_b64_e32 v[54:55], 0
	v_mov_b64_e32 v[52:53], 0
	v_mov_b64_e32 v[46:47], 0
	v_mov_b64_e32 v[44:45], 0
	v_mov_b64_e32 v[38:39], 0
	v_mov_b64_e32 v[36:37], 0
	v_mov_b64_e32 v[30:31], 0
	v_mov_b64_e32 v[28:29], 0
	v_mov_b64_e32 v[22:23], 0
	v_mov_b64_e32 v[20:21], 0
	v_mov_b64_e32 v[14:15], 0
	v_mov_b64_e32 v[12:13], 0
	v_mov_b64_e32 v[6:7], 0
	v_mov_b64_e32 v[4:5], 0
	s_branch .LBB0_195

.LBB0_275:
	s_andn2_b64 vcc, exec, s[48:49]
	s_cbranch_vccnz .Lcoldzero_2
	s_add_u32 s10, s6, 0x100
	s_addc_u32 s11, s7, 0
	s_add_u32 s6, s8, 0x80
	v_mov_b32_e32 v0, 0
	s_addc_u32 s7, s9, 0
	s_mov_b32 s8, 0
	v_mov_b32_e32 v1, v0
	v_mov_b64_e32 v[2:3], 0
	v_mov_b64_e32 v[4:5], 0
	v_mov_b64_e32 v[6:7], 0
	v_mov_b64_e32 v[16:17], 0
	v_mov_b64_e32 v[18:19], 0
	v_mov_b64_e32 v[20:21], 0
	v_mov_b64_e32 v[22:23], 0
	v_mov_b64_e32 v[32:33], 0
	v_mov_b64_e32 v[34:35], 0
	v_mov_b64_e32 v[36:37], 0
	v_mov_b64_e32 v[38:39], 0
	v_mov_b64_e32 v[48:49], 0
	v_mov_b64_e32 v[50:51], 0
	v_mov_b64_e32 v[52:53], 0
	v_mov_b64_e32 v[54:55], 0
	v_mov_b64_e32 v[8:9], 0
	v_mov_b64_e32 v[10:11], 0
	v_mov_b64_e32 v[12:13], 0
	v_mov_b64_e32 v[14:15], 0
	v_mov_b64_e32 v[24:25], 0
	v_mov_b64_e32 v[26:27], 0
	v_mov_b64_e32 v[28:29], 0
	v_mov_b64_e32 v[30:31], 0
	v_mov_b64_e32 v[40:41], 0
	v_mov_b64_e32 v[42:43], 0
	v_mov_b64_e32 v[44:45], 0
	v_mov_b64_e32 v[46:47], 0
	v_mov_b64_e32 v[56:57], 0
	v_mov_b64_e32 v[58:59], 0
	v_mov_b64_e32 v[60:61], 0
	v_mov_b64_e32 v[62:63], 0
	v_mov_b64_e32 v[64:65], 0
	v_mov_b64_e32 v[66:67], 0
	v_mov_b64_e32 v[68:69], 0
	v_mov_b64_e32 v[70:71], 0
	v_mov_b64_e32 v[80:81], 0
	v_mov_b64_e32 v[82:83], 0
	v_mov_b64_e32 v[84:85], 0
	v_mov_b64_e32 v[86:87], 0
	v_mov_b64_e32 v[96:97], 0
	v_mov_b64_e32 v[98:99], 0
	v_mov_b64_e32 v[100:101], 0
	v_mov_b64_e32 v[102:103], 0
	v_mov_b64_e32 v[112:113], 0
	v_mov_b64_e32 v[114:115], 0
	v_mov_b64_e32 v[116:117], 0
	v_mov_b64_e32 v[118:119], 0
	v_mov_b64_e32 v[72:73], 0
	v_mov_b64_e32 v[74:75], 0
	v_mov_b64_e32 v[76:77], 0
	v_mov_b64_e32 v[78:79], 0
	v_mov_b64_e32 v[88:89], 0
	v_mov_b64_e32 v[90:91], 0
	v_mov_b64_e32 v[92:93], 0
	v_mov_b64_e32 v[94:95], 0
	v_mov_b64_e32 v[104:105], 0
	v_mov_b64_e32 v[106:107], 0
	v_mov_b64_e32 v[108:109], 0
	v_mov_b64_e32 v[110:111], 0
	v_mov_b64_e32 v[120:121], 0
	v_mov_b64_e32 v[122:123], 0
	v_mov_b64_e32 v[124:125], 0
	v_mov_b64_e32 v[126:127], 0

.Lcoldzero_2:
	v_mov_b32_e32 v127, 0
	v_mov_b32_e32 v126, v127
	v_mov_b64_e32 v[124:125], 0
	v_mov_b64_e32 v[122:123], 0
	v_mov_b64_e32 v[120:121], 0
	v_mov_b64_e32 v[110:111], 0
	v_mov_b64_e32 v[108:109], 0
	v_mov_b64_e32 v[106:107], 0
	v_mov_b64_e32 v[104:105], 0
	v_mov_b64_e32 v[94:95], 0
	v_mov_b64_e32 v[92:93], 0
	v_mov_b64_e32 v[90:91], 0
	v_mov_b64_e32 v[88:89], 0
	v_mov_b64_e32 v[78:79], 0
	v_mov_b64_e32 v[76:77], 0
	v_mov_b64_e32 v[74:75], 0
	v_mov_b64_e32 v[72:73], 0
	v_mov_b64_e32 v[118:119], 0
	v_mov_b64_e32 v[116:117], 0
	v_mov_b64_e32 v[114:115], 0
	v_mov_b64_e32 v[112:113], 0
	v_mov_b64_e32 v[102:103], 0
	v_mov_b64_e32 v[100:101], 0
	v_mov_b64_e32 v[98:99], 0
	v_mov_b64_e32 v[96:97], 0
	v_mov_b64_e32 v[86:87], 0
	v_mov_b64_e32 v[84:85], 0
	v_mov_b64_e32 v[82:83], 0
	v_mov_b64_e32 v[80:81], 0
	v_mov_b64_e32 v[70:71], 0
	v_mov_b64_e32 v[68:69], 0
	v_mov_b64_e32 v[66:67], 0
	v_mov_b64_e32 v[64:65], 0
	v_mov_b64_e32 v[62:63], 0
	v_mov_b64_e32 v[60:61], 0
	v_mov_b64_e32 v[58:59], 0
	v_mov_b64_e32 v[56:57], 0
	v_mov_b64_e32 v[46:47], 0
	v_mov_b64_e32 v[44:45], 0
	v_mov_b64_e32 v[42:43], 0
	v_mov_b64_e32 v[40:41], 0
	v_mov_b64_e32 v[30:31], 0
	v_mov_b64_e32 v[28:29], 0
	v_mov_b64_e32 v[26:27], 0
	v_mov_b64_e32 v[24:25], 0
	v_mov_b64_e32 v[14:15], 0
	v_mov_b64_e32 v[12:13], 0
	v_mov_b64_e32 v[10:11], 0
	v_mov_b64_e32 v[8:9], 0
	v_mov_b64_e32 v[54:55], 0
	v_mov_b64_e32 v[52:53], 0
	v_mov_b64_e32 v[50:51], 0
	v_mov_b64_e32 v[48:49], 0
	v_mov_b64_e32 v[38:39], 0
	v_mov_b64_e32 v[36:37], 0
	v_mov_b64_e32 v[34:35], 0
	v_mov_b64_e32 v[32:33], 0
	v_mov_b64_e32 v[22:23], 0
	v_mov_b64_e32 v[20:21], 0
	v_mov_b64_e32 v[18:19], 0
	v_mov_b64_e32 v[16:17], 0
	v_mov_b64_e32 v[6:7], 0
	v_mov_b64_e32 v[4:5], 0
	v_mov_b64_e32 v[2:3], 0
	v_mov_b64_e32 v[0:1], 0
	s_branch .LBB0_264

.LBB0_403:
	s_andn2_b64 vcc, exec, s[40:41]
	s_cbranch_vccnz .Lcoldzero_3
	s_add_u32 s10, s6, 0x100
	s_addc_u32 s11, s7, 0
	s_add_u32 s6, s8, 0x80
	v_mov_b32_e32 v0, 0
	s_addc_u32 s7, s9, 0
	s_mov_b32 s8, 0
	v_mov_b32_e32 v1, v0
	v_mov_b64_e32 v[2:3], 0
	v_mov_b64_e32 v[4:5], 0
	v_mov_b64_e32 v[6:7], 0
	v_mov_b64_e32 v[16:17], 0
	v_mov_b64_e32 v[18:19], 0
	v_mov_b64_e32 v[20:21], 0
	v_mov_b64_e32 v[22:23], 0
	v_mov_b64_e32 v[32:33], 0
	v_mov_b64_e32 v[34:35], 0
	v_mov_b64_e32 v[36:37], 0
	v_mov_b64_e32 v[38:39], 0
	v_mov_b64_e32 v[48:49], 0
	v_mov_b64_e32 v[50:51], 0
	v_mov_b64_e32 v[52:53], 0
	v_mov_b64_e32 v[54:55], 0
	v_mov_b64_e32 v[8:9], 0
	v_mov_b64_e32 v[10:11], 0
	v_mov_b64_e32 v[12:13], 0
	v_mov_b64_e32 v[14:15], 0
	v_mov_b64_e32 v[24:25], 0
	v_mov_b64_e32 v[26:27], 0
	v_mov_b64_e32 v[28:29], 0
	v_mov_b64_e32 v[30:31], 0
	v_mov_b64_e32 v[40:41], 0
	v_mov_b64_e32 v[42:43], 0
	v_mov_b64_e32 v[44:45], 0
	v_mov_b64_e32 v[46:47], 0
	v_mov_b64_e32 v[56:57], 0
	v_mov_b64_e32 v[58:59], 0
	v_mov_b64_e32 v[60:61], 0
	v_mov_b64_e32 v[62:63], 0
	v_mov_b64_e32 v[64:65], 0
	v_mov_b64_e32 v[66:67], 0
	v_mov_b64_e32 v[68:69], 0
	v_mov_b64_e32 v[70:71], 0
	v_mov_b64_e32 v[80:81], 0
	v_mov_b64_e32 v[82:83], 0
	v_mov_b64_e32 v[84:85], 0
	v_mov_b64_e32 v[86:87], 0
	v_mov_b64_e32 v[96:97], 0
	v_mov_b64_e32 v[98:99], 0
	v_mov_b64_e32 v[100:101], 0
	v_mov_b64_e32 v[102:103], 0
	v_mov_b64_e32 v[112:113], 0
	v_mov_b64_e32 v[114:115], 0
	v_mov_b64_e32 v[116:117], 0
	v_mov_b64_e32 v[118:119], 0
	v_mov_b64_e32 v[72:73], 0
	v_mov_b64_e32 v[74:75], 0
	v_mov_b64_e32 v[76:77], 0
	v_mov_b64_e32 v[78:79], 0
	v_mov_b64_e32 v[88:89], 0
	v_mov_b64_e32 v[90:91], 0
	v_mov_b64_e32 v[92:93], 0
	v_mov_b64_e32 v[94:95], 0
	v_mov_b64_e32 v[104:105], 0
	v_mov_b64_e32 v[106:107], 0
	v_mov_b64_e32 v[108:109], 0
	v_mov_b64_e32 v[110:111], 0
	v_mov_b64_e32 v[124:125], 0
	v_mov_b64_e32 v[126:127], 0
	v_mov_b64_e32 v[120:121], 0
	v_mov_b64_e32 v[122:123], 0

.Lcoldzero_3:
	v_mov_b32_e32 v123, 0
	v_mov_b32_e32 v122, v123
	v_mov_b64_e32 v[120:121], 0
	v_mov_b64_e32 v[126:127], 0
	v_mov_b64_e32 v[124:125], 0
	v_mov_b64_e32 v[110:111], 0
	v_mov_b64_e32 v[108:109], 0
	v_mov_b64_e32 v[106:107], 0
	v_mov_b64_e32 v[104:105], 0
	v_mov_b64_e32 v[94:95], 0
	v_mov_b64_e32 v[92:93], 0
	v_mov_b64_e32 v[90:91], 0
	v_mov_b64_e32 v[88:89], 0
	v_mov_b64_e32 v[78:79], 0
	v_mov_b64_e32 v[76:77], 0
	v_mov_b64_e32 v[74:75], 0
	v_mov_b64_e32 v[72:73], 0
	v_mov_b64_e32 v[118:119], 0
	v_mov_b64_e32 v[116:117], 0
	v_mov_b64_e32 v[114:115], 0
	v_mov_b64_e32 v[112:113], 0
	v_mov_b64_e32 v[102:103], 0
	v_mov_b64_e32 v[100:101], 0
	v_mov_b64_e32 v[98:99], 0
	v_mov_b64_e32 v[96:97], 0
	v_mov_b64_e32 v[86:87], 0
	v_mov_b64_e32 v[84:85], 0
	v_mov_b64_e32 v[82:83], 0
	v_mov_b64_e32 v[80:81], 0
	v_mov_b64_e32 v[70:71], 0
	v_mov_b64_e32 v[68:69], 0
	v_mov_b64_e32 v[66:67], 0
	v_mov_b64_e32 v[64:65], 0
	v_mov_b64_e32 v[62:63], 0
	v_mov_b64_e32 v[60:61], 0
	v_mov_b64_e32 v[58:59], 0
	v_mov_b64_e32 v[56:57], 0
	v_mov_b64_e32 v[46:47], 0
	v_mov_b64_e32 v[44:45], 0
	v_mov_b64_e32 v[42:43], 0
	v_mov_b64_e32 v[40:41], 0
	v_mov_b64_e32 v[30:31], 0
	v_mov_b64_e32 v[28:29], 0
	v_mov_b64_e32 v[26:27], 0
	v_mov_b64_e32 v[24:25], 0
	v_mov_b64_e32 v[14:15], 0
	v_mov_b64_e32 v[12:13], 0
	v_mov_b64_e32 v[10:11], 0
	v_mov_b64_e32 v[8:9], 0
	v_mov_b64_e32 v[54:55], 0
	v_mov_b64_e32 v[52:53], 0
	v_mov_b64_e32 v[50:51], 0
	v_mov_b64_e32 v[48:49], 0
	v_mov_b64_e32 v[38:39], 0
	v_mov_b64_e32 v[36:37], 0
	v_mov_b64_e32 v[34:35], 0
	v_mov_b64_e32 v[32:33], 0
	v_mov_b64_e32 v[22:23], 0
	v_mov_b64_e32 v[20:21], 0
	v_mov_b64_e32 v[18:19], 0
	v_mov_b64_e32 v[16:17], 0
	v_mov_b64_e32 v[6:7], 0
	v_mov_b64_e32 v[4:5], 0
	v_mov_b64_e32 v[2:3], 0
	v_mov_b64_e32 v[0:1], 0
	s_branch .LBB0_392

.LBB0_933:
	s_andn2_b64 vcc, exec, s[40:41]
	s_cbranch_vccnz .Lcoldzero_5
	s_add_u32 s10, s6, 0x100
	s_addc_u32 s11, s7, 0
	s_add_u32 s6, s8, 0x80
	v_mov_b32_e32 v0, 0
	s_addc_u32 s7, s9, 0
	s_mov_b32 s8, 0
	v_mov_b32_e32 v1, v0
	v_mov_b64_e32 v[2:3], 0
	v_mov_b64_e32 v[4:5], 0
	v_mov_b64_e32 v[6:7], 0
	v_mov_b64_e32 v[16:17], 0
	v_mov_b64_e32 v[18:19], 0
	v_mov_b64_e32 v[20:21], 0
	v_mov_b64_e32 v[22:23], 0
	v_mov_b64_e32 v[32:33], 0
	v_mov_b64_e32 v[34:35], 0
	v_mov_b64_e32 v[36:37], 0
	v_mov_b64_e32 v[38:39], 0
	v_mov_b64_e32 v[48:49], 0
	v_mov_b64_e32 v[50:51], 0
	v_mov_b64_e32 v[52:53], 0
	v_mov_b64_e32 v[54:55], 0
	v_mov_b64_e32 v[8:9], 0
	v_mov_b64_e32 v[10:11], 0
	v_mov_b64_e32 v[12:13], 0
	v_mov_b64_e32 v[14:15], 0
	v_mov_b64_e32 v[24:25], 0
	v_mov_b64_e32 v[26:27], 0
	v_mov_b64_e32 v[28:29], 0
	v_mov_b64_e32 v[30:31], 0
	v_mov_b64_e32 v[40:41], 0
	v_mov_b64_e32 v[42:43], 0
	v_mov_b64_e32 v[44:45], 0
	v_mov_b64_e32 v[46:47], 0
	v_mov_b64_e32 v[56:57], 0
	v_mov_b64_e32 v[58:59], 0
	v_mov_b64_e32 v[60:61], 0
	v_mov_b64_e32 v[62:63], 0
	v_mov_b64_e32 v[64:65], 0
	v_mov_b64_e32 v[66:67], 0
	v_mov_b64_e32 v[68:69], 0
	v_mov_b64_e32 v[70:71], 0
	v_mov_b64_e32 v[84:85], 0
	v_mov_b64_e32 v[86:87], 0
	v_mov_b64_e32 v[88:89], 0
	v_mov_b64_e32 v[90:91], 0
	v_mov_b64_e32 v[100:101], 0
	v_mov_b64_e32 v[102:103], 0
	v_mov_b64_e32 v[104:105], 0
	v_mov_b64_e32 v[106:107], 0
	v_mov_b64_e32 v[116:117], 0
	v_mov_b64_e32 v[118:119], 0
	v_mov_b64_e32 v[120:121], 0
	v_mov_b64_e32 v[122:123], 0
	v_mov_b64_e32 v[72:73], 0
	v_mov_b64_e32 v[74:75], 0
	v_mov_b64_e32 v[76:77], 0
	v_mov_b64_e32 v[78:79], 0
	v_mov_b64_e32 v[92:93], 0
	v_mov_b64_e32 v[94:95], 0
	v_mov_b64_e32 v[96:97], 0
	v_mov_b64_e32 v[98:99], 0
	v_mov_b64_e32 v[108:109], 0
	v_mov_b64_e32 v[110:111], 0
	v_mov_b64_e32 v[112:113], 0
	v_mov_b64_e32 v[114:115], 0
	v_mov_b64_e32 v[124:125], 0
	v_mov_b64_e32 v[126:127], 0
	v_mov_b64_e32 v[128:129], 0
	v_mov_b64_e32 v[130:131], 0

.Lcoldzero_5:
	v_mov_b32_e32 v131, 0
	v_mov_b32_e32 v130, v131
	v_mov_b64_e32 v[128:129], 0
	v_mov_b64_e32 v[126:127], 0
	v_mov_b64_e32 v[124:125], 0
	v_mov_b64_e32 v[114:115], 0
	v_mov_b64_e32 v[112:113], 0
	v_mov_b64_e32 v[110:111], 0
	v_mov_b64_e32 v[108:109], 0
	v_mov_b64_e32 v[98:99], 0
	v_mov_b64_e32 v[96:97], 0
	v_mov_b64_e32 v[94:95], 0
	v_mov_b64_e32 v[92:93], 0
	v_mov_b64_e32 v[78:79], 0
	v_mov_b64_e32 v[76:77], 0
	v_mov_b64_e32 v[74:75], 0
	v_mov_b64_e32 v[72:73], 0
	v_mov_b64_e32 v[122:123], 0
	v_mov_b64_e32 v[120:121], 0
	v_mov_b64_e32 v[118:119], 0
	v_mov_b64_e32 v[116:117], 0
	v_mov_b64_e32 v[106:107], 0
	v_mov_b64_e32 v[104:105], 0
	v_mov_b64_e32 v[102:103], 0
	v_mov_b64_e32 v[100:101], 0
	v_mov_b64_e32 v[90:91], 0
	v_mov_b64_e32 v[88:89], 0
	v_mov_b64_e32 v[86:87], 0
	v_mov_b64_e32 v[84:85], 0
	v_mov_b64_e32 v[70:71], 0
	v_mov_b64_e32 v[68:69], 0
	v_mov_b64_e32 v[66:67], 0
	v_mov_b64_e32 v[64:65], 0
	v_mov_b64_e32 v[62:63], 0
	v_mov_b64_e32 v[60:61], 0
	v_mov_b64_e32 v[58:59], 0
	v_mov_b64_e32 v[56:57], 0
	v_mov_b64_e32 v[46:47], 0
	v_mov_b64_e32 v[44:45], 0
	v_mov_b64_e32 v[42:43], 0
	v_mov_b64_e32 v[40:41], 0
	v_mov_b64_e32 v[30:31], 0
	v_mov_b64_e32 v[28:29], 0
	v_mov_b64_e32 v[26:27], 0
	v_mov_b64_e32 v[24:25], 0
	v_mov_b64_e32 v[14:15], 0
	v_mov_b64_e32 v[12:13], 0
	v_mov_b64_e32 v[10:11], 0
	v_mov_b64_e32 v[8:9], 0
	v_mov_b64_e32 v[54:55], 0
	v_mov_b64_e32 v[52:53], 0
	v_mov_b64_e32 v[50:51], 0
	v_mov_b64_e32 v[48:49], 0
	v_mov_b64_e32 v[38:39], 0
	v_mov_b64_e32 v[36:37], 0
	v_mov_b64_e32 v[34:35], 0
	v_mov_b64_e32 v[32:33], 0
	v_mov_b64_e32 v[22:23], 0
	v_mov_b64_e32 v[20:21], 0
	v_mov_b64_e32 v[18:19], 0
	v_mov_b64_e32 v[16:17], 0
	v_mov_b64_e32 v[6:7], 0
	v_mov_b64_e32 v[4:5], 0
	v_mov_b64_e32 v[2:3], 0
	v_mov_b64_e32 v[0:1], 0
	s_branch .LBB0_922

.LBB0_1057:
	s_andn2_b64 vcc, exec, s[46:47]
	s_cbranch_vccnz .Lcoldzero_6
	s_add_u32 s10, s6, 0x100
	s_addc_u32 s11, s7, 0
	s_add_u32 s6, s8, 0x80
	v_mov_b32_e32 v4, 0
	s_addc_u32 s7, s9, 0
	s_mov_b32 s8, 0
	v_mov_b32_e32 v5, v4
	v_mov_b64_e32 v[6:7], 0
	v_mov_b64_e32 v[12:13], 0
	v_mov_b64_e32 v[14:15], 0
	v_mov_b64_e32 v[20:21], 0
	v_mov_b64_e32 v[22:23], 0
	v_mov_b64_e32 v[28:29], 0
	v_mov_b64_e32 v[30:31], 0
	v_mov_b64_e32 v[36:37], 0
	v_mov_b64_e32 v[38:39], 0
	v_mov_b64_e32 v[44:45], 0
	v_mov_b64_e32 v[46:47], 0
	v_mov_b64_e32 v[52:53], 0
	v_mov_b64_e32 v[54:55], 0
	v_mov_b64_e32 v[60:61], 0
	v_mov_b64_e32 v[62:63], 0
	v_mov_b64_e32 v[0:1], 0
	v_mov_b64_e32 v[2:3], 0
	v_mov_b64_e32 v[8:9], 0
	v_mov_b64_e32 v[10:11], 0
	v_mov_b64_e32 v[16:17], 0
	v_mov_b64_e32 v[18:19], 0
	v_mov_b64_e32 v[24:25], 0
	v_mov_b64_e32 v[26:27], 0
	v_mov_b64_e32 v[32:33], 0
	v_mov_b64_e32 v[34:35], 0
	v_mov_b64_e32 v[40:41], 0
	v_mov_b64_e32 v[42:43], 0
	v_mov_b64_e32 v[48:49], 0
	v_mov_b64_e32 v[50:51], 0
	v_mov_b64_e32 v[56:57], 0
	v_mov_b64_e32 v[58:59], 0
	v_mov_b64_e32 v[68:69], 0
	v_mov_b64_e32 v[70:71], 0
	v_mov_b64_e32 v[76:77], 0
	v_mov_b64_e32 v[78:79], 0
	v_mov_b64_e32 v[84:85], 0
	v_mov_b64_e32 v[86:87], 0
	v_mov_b64_e32 v[92:93], 0
	v_mov_b64_e32 v[94:95], 0
	v_mov_b64_e32 v[100:101], 0
	v_mov_b64_e32 v[102:103], 0
	v_mov_b64_e32 v[108:109], 0
	v_mov_b64_e32 v[110:111], 0
	v_mov_b64_e32 v[116:117], 0
	v_mov_b64_e32 v[118:119], 0
	v_mov_b64_e32 v[124:125], 0
	v_mov_b64_e32 v[126:127], 0
	v_mov_b64_e32 v[64:65], 0
	v_mov_b64_e32 v[66:67], 0
	v_mov_b64_e32 v[72:73], 0
	v_mov_b64_e32 v[74:75], 0
	v_mov_b64_e32 v[80:81], 0
	v_mov_b64_e32 v[82:83], 0
	v_mov_b64_e32 v[88:89], 0
	v_mov_b64_e32 v[90:91], 0
	v_mov_b64_e32 v[96:97], 0
	v_mov_b64_e32 v[98:99], 0
	v_mov_b64_e32 v[104:105], 0
	v_mov_b64_e32 v[106:107], 0
	v_mov_b64_e32 v[112:113], 0
	v_mov_b64_e32 v[114:115], 0
	v_mov_b64_e32 v[120:121], 0
	v_mov_b64_e32 v[122:123], 0

.LBB0_1130:
	s_andn2_b64 vcc, exec, s[4:5]
	s_cbranch_vccnz .Lcoldzero_7
	s_add_u32 s10, s6, 0x100
	s_addc_u32 s11, s7, 0
	s_add_u32 s6, s8, 0x80
	v_mov_b32_e32 v0, 0
	s_addc_u32 s7, s9, 0
	s_mov_b32 s8, 0
	v_mov_b32_e32 v1, v0
	v_mov_b64_e32 v[2:3], 0
	v_mov_b64_e32 v[4:5], 0
	v_mov_b64_e32 v[6:7], 0
	v_mov_b64_e32 v[16:17], 0
	v_mov_b64_e32 v[18:19], 0
	v_mov_b64_e32 v[20:21], 0
	v_mov_b64_e32 v[22:23], 0
	v_mov_b64_e32 v[32:33], 0
	v_mov_b64_e32 v[34:35], 0
	v_mov_b64_e32 v[36:37], 0
	v_mov_b64_e32 v[38:39], 0
	v_mov_b64_e32 v[48:49], 0
	v_mov_b64_e32 v[50:51], 0
	v_mov_b64_e32 v[52:53], 0
	v_mov_b64_e32 v[54:55], 0
	v_mov_b64_e32 v[8:9], 0
	v_mov_b64_e32 v[10:11], 0
	v_mov_b64_e32 v[12:13], 0
	v_mov_b64_e32 v[14:15], 0
	v_mov_b64_e32 v[24:25], 0
	v_mov_b64_e32 v[26:27], 0
	v_mov_b64_e32 v[28:29], 0
	v_mov_b64_e32 v[30:31], 0
	v_mov_b64_e32 v[40:41], 0
	v_mov_b64_e32 v[42:43], 0
	v_mov_b64_e32 v[44:45], 0
	v_mov_b64_e32 v[46:47], 0
	v_mov_b64_e32 v[56:57], 0
	v_mov_b64_e32 v[58:59], 0
	v_mov_b64_e32 v[60:61], 0
	v_mov_b64_e32 v[62:63], 0
	v_mov_b64_e32 v[64:65], 0
	v_mov_b64_e32 v[66:67], 0
	v_mov_b64_e32 v[68:69], 0
	v_mov_b64_e32 v[70:71], 0
	v_mov_b64_e32 v[80:81], 0
	v_mov_b64_e32 v[82:83], 0
	v_mov_b64_e32 v[84:85], 0
	v_mov_b64_e32 v[86:87], 0
	v_mov_b64_e32 v[96:97], 0
	v_mov_b64_e32 v[98:99], 0
	v_mov_b64_e32 v[100:101], 0
	v_mov_b64_e32 v[102:103], 0
	v_mov_b64_e32 v[112:113], 0
	v_mov_b64_e32 v[114:115], 0
	v_mov_b64_e32 v[116:117], 0
	v_mov_b64_e32 v[118:119], 0
	v_mov_b64_e32 v[72:73], 0
	v_mov_b64_e32 v[74:75], 0
	v_mov_b64_e32 v[76:77], 0
	v_mov_b64_e32 v[78:79], 0
	v_mov_b64_e32 v[88:89], 0
	v_mov_b64_e32 v[90:91], 0
	v_mov_b64_e32 v[92:93], 0
	v_mov_b64_e32 v[94:95], 0
	v_mov_b64_e32 v[104:105], 0
	v_mov_b64_e32 v[106:107], 0
	v_mov_b64_e32 v[108:109], 0
	v_mov_b64_e32 v[110:111], 0
	v_mov_b64_e32 v[120:121], 0
	v_mov_b64_e32 v[122:123], 0
	v_mov_b64_e32 v[124:125], 0
	v_mov_b64_e32 v[126:127], 0
